# v091 + P2 pass 1: rolling load stream (16 loads kept in flight across all 32 channel groups instead of two drain-and-refill batches), same accumulation order
# speedup vs baseline: 1.0016x; 1.0016x over previous
.LBB0_390:
	v_lshl_add_u64 v[12:13], v[10:11], 0, s[42:43]
	s_mov_b32 s8, 0x100000
	s_mov_b32 s9, 0
	global_load_dwordx4 v[176:179], v[12:13], off
	v_lshl_add_u64 v[12:13], v[12:13], 0, s[8:9]
	global_load_dwordx4 v[180:183], v[12:13], off
	v_lshl_add_u64 v[12:13], v[12:13], 0, s[8:9]
	global_load_dwordx4 v[184:187], v[12:13], off
	v_lshl_add_u64 v[12:13], v[12:13], 0, s[8:9]
	global_load_dwordx4 v[188:191], v[12:13], off
	v_lshl_add_u64 v[12:13], v[12:13], 0, s[8:9]
	global_load_dwordx4 v[192:195], v[12:13], off
	v_lshl_add_u64 v[12:13], v[12:13], 0, s[8:9]
	global_load_dwordx4 v[196:199], v[12:13], off
	v_lshl_add_u64 v[12:13], v[12:13], 0, s[8:9]
	global_load_dwordx4 v[200:203], v[12:13], off
	v_lshl_add_u64 v[12:13], v[12:13], 0, s[8:9]
	global_load_dwordx4 v[204:207], v[12:13], off
	v_lshl_add_u64 v[12:13], v[12:13], 0, s[8:9]
	global_load_dwordx4 v[208:211], v[12:13], off
	v_lshl_add_u64 v[12:13], v[12:13], 0, s[8:9]
	global_load_dwordx4 v[212:215], v[12:13], off
	v_lshl_add_u64 v[12:13], v[12:13], 0, s[8:9]
	global_load_dwordx4 v[216:219], v[12:13], off
	v_lshl_add_u64 v[12:13], v[12:13], 0, s[8:9]
	global_load_dwordx4 v[220:223], v[12:13], off
	v_lshl_add_u64 v[12:13], v[12:13], 0, s[8:9]
	global_load_dwordx4 v[224:227], v[12:13], off
	v_lshl_add_u64 v[12:13], v[12:13], 0, s[8:9]
	global_load_dwordx4 v[228:231], v[12:13], off
	v_lshl_add_u64 v[12:13], v[12:13], 0, s[8:9]
	global_load_dwordx4 v[232:235], v[12:13], off
	v_lshl_add_u64 v[12:13], v[12:13], 0, s[8:9]
	global_load_dwordx4 v[236:239], v[12:13], off
	v_lshl_add_u64 v[12:13], v[12:13], 0, s[8:9]
	s_waitcnt vmcnt(15)
	v_lshlrev_b32_e32 v20, 16, v176
	v_and_b32_e32 v21, 0xffff0000, v176
	v_lshlrev_b32_e32 v22, 16, v177
	v_and_b32_e32 v23, 0xffff0000, v177
	v_lshlrev_b32_e32 v24, 16, v178
	v_and_b32_e32 v25, 0xffff0000, v178
	v_lshlrev_b32_e32 v26, 16, v179
	v_and_b32_e32 v27, 0xffff0000, v179
	v_pk_fma_f32 v[8:9], v[20:21], v[20:21], v[8:9]
	v_pk_fma_f32 v[6:7], v[22:23], v[22:23], v[6:7]
	v_pk_fma_f32 v[4:5], v[24:25], v[24:25], v[4:5]
	v_pk_fma_f32 v[2:3], v[26:27], v[26:27], v[2:3]
	global_load_dwordx4 v[176:179], v[12:13], off
	v_lshl_add_u64 v[12:13], v[12:13], 0, s[8:9]
	s_waitcnt vmcnt(15)
	v_lshlrev_b32_e32 v20, 16, v180
	v_and_b32_e32 v21, 0xffff0000, v180
	v_lshlrev_b32_e32 v22, 16, v181
	v_and_b32_e32 v23, 0xffff0000, v181
	v_lshlrev_b32_e32 v24, 16, v182
	v_and_b32_e32 v25, 0xffff0000, v182
	v_lshlrev_b32_e32 v26, 16, v183
	v_and_b32_e32 v27, 0xffff0000, v183
	v_pk_fma_f32 v[8:9], v[20:21], v[20:21], v[8:9]
	v_pk_fma_f32 v[6:7], v[22:23], v[22:23], v[6:7]
	v_pk_fma_f32 v[4:5], v[24:25], v[24:25], v[4:5]
	v_pk_fma_f32 v[2:3], v[26:27], v[26:27], v[2:3]
	global_load_dwordx4 v[180:183], v[12:13], off
	v_lshl_add_u64 v[12:13], v[12:13], 0, s[8:9]
	s_waitcnt vmcnt(15)
	v_lshlrev_b32_e32 v20, 16, v184
	v_and_b32_e32 v21, 0xffff0000, v184
	v_lshlrev_b32_e32 v22, 16, v185
	v_and_b32_e32 v23, 0xffff0000, v185
	v_lshlrev_b32_e32 v24, 16, v186
	v_and_b32_e32 v25, 0xffff0000, v186
	v_lshlrev_b32_e32 v26, 16, v187
	v_and_b32_e32 v27, 0xffff0000, v187
	v_pk_fma_f32 v[8:9], v[20:21], v[20:21], v[8:9]
	v_pk_fma_f32 v[6:7], v[22:23], v[22:23], v[6:7]
	v_pk_fma_f32 v[4:5], v[24:25], v[24:25], v[4:5]
	v_pk_fma_f32 v[2:3], v[26:27], v[26:27], v[2:3]
	global_load_dwordx4 v[184:187], v[12:13], off
	v_lshl_add_u64 v[12:13], v[12:13], 0, s[8:9]
	s_waitcnt vmcnt(15)
	v_lshlrev_b32_e32 v20, 16, v188
	v_and_b32_e32 v21, 0xffff0000, v188
	v_lshlrev_b32_e32 v22, 16, v189
	v_and_b32_e32 v23, 0xffff0000, v189
	v_lshlrev_b32_e32 v24, 16, v190
	v_and_b32_e32 v25, 0xffff0000, v190
	v_lshlrev_b32_e32 v26, 16, v191
	v_and_b32_e32 v27, 0xffff0000, v191
	v_pk_fma_f32 v[8:9], v[20:21], v[20:21], v[8:9]
	v_pk_fma_f32 v[6:7], v[22:23], v[22:23], v[6:7]
	v_pk_fma_f32 v[4:5], v[24:25], v[24:25], v[4:5]
	v_pk_fma_f32 v[2:3], v[26:27], v[26:27], v[2:3]
	global_load_dwordx4 v[188:191], v[12:13], off
	v_lshl_add_u64 v[12:13], v[12:13], 0, s[8:9]
	s_waitcnt vmcnt(15)
	v_lshlrev_b32_e32 v20, 16, v192
	v_and_b32_e32 v21, 0xffff0000, v192
	v_lshlrev_b32_e32 v22, 16, v193
	v_and_b32_e32 v23, 0xffff0000, v193
	v_lshlrev_b32_e32 v24, 16, v194
	v_and_b32_e32 v25, 0xffff0000, v194
	v_lshlrev_b32_e32 v26, 16, v195
	v_and_b32_e32 v27, 0xffff0000, v195
	v_pk_fma_f32 v[8:9], v[20:21], v[20:21], v[8:9]
	v_pk_fma_f32 v[6:7], v[22:23], v[22:23], v[6:7]
	v_pk_fma_f32 v[4:5], v[24:25], v[24:25], v[4:5]
	v_pk_fma_f32 v[2:3], v[26:27], v[26:27], v[2:3]
	global_load_dwordx4 v[192:195], v[12:13], off
	v_lshl_add_u64 v[12:13], v[12:13], 0, s[8:9]
	s_waitcnt vmcnt(15)
	v_lshlrev_b32_e32 v20, 16, v196
	v_and_b32_e32 v21, 0xffff0000, v196
	v_lshlrev_b32_e32 v22, 16, v197
	v_and_b32_e32 v23, 0xffff0000, v197
	v_lshlrev_b32_e32 v24, 16, v198
	v_and_b32_e32 v25, 0xffff0000, v198
	v_lshlrev_b32_e32 v26, 16, v199
	v_and_b32_e32 v27, 0xffff0000, v199
	v_pk_fma_f32 v[8:9], v[20:21], v[20:21], v[8:9]
	v_pk_fma_f32 v[6:7], v[22:23], v[22:23], v[6:7]
	v_pk_fma_f32 v[4:5], v[24:25], v[24:25], v[4:5]
	v_pk_fma_f32 v[2:3], v[26:27], v[26:27], v[2:3]
	global_load_dwordx4 v[196:199], v[12:13], off
	v_lshl_add_u64 v[12:13], v[12:13], 0, s[8:9]
	s_waitcnt vmcnt(15)
	v_lshlrev_b32_e32 v20, 16, v200
	v_and_b32_e32 v21, 0xffff0000, v200
	v_lshlrev_b32_e32 v22, 16, v201
	v_and_b32_e32 v23, 0xffff0000, v201
	v_lshlrev_b32_e32 v24, 16, v202
	v_and_b32_e32 v25, 0xffff0000, v202
	v_lshlrev_b32_e32 v26, 16, v203
	v_and_b32_e32 v27, 0xffff0000, v203
	v_pk_fma_f32 v[8:9], v[20:21], v[20:21], v[8:9]
	v_pk_fma_f32 v[6:7], v[22:23], v[22:23], v[6:7]
	v_pk_fma_f32 v[4:5], v[24:25], v[24:25], v[4:5]
	v_pk_fma_f32 v[2:3], v[26:27], v[26:27], v[2:3]
	global_load_dwordx4 v[200:203], v[12:13], off
	v_lshl_add_u64 v[12:13], v[12:13], 0, s[8:9]
	s_waitcnt vmcnt(15)
	v_lshlrev_b32_e32 v20, 16, v204
	v_and_b32_e32 v21, 0xffff0000, v204
	v_lshlrev_b32_e32 v22, 16, v205
	v_and_b32_e32 v23, 0xffff0000, v205
	v_lshlrev_b32_e32 v24, 16, v206
	v_and_b32_e32 v25, 0xffff0000, v206
	v_lshlrev_b32_e32 v26, 16, v207
	v_and_b32_e32 v27, 0xffff0000, v207
	v_pk_fma_f32 v[8:9], v[20:21], v[20:21], v[8:9]
	v_pk_fma_f32 v[6:7], v[22:23], v[22:23], v[6:7]
	v_pk_fma_f32 v[4:5], v[24:25], v[24:25], v[4:5]
	v_pk_fma_f32 v[2:3], v[26:27], v[26:27], v[2:3]
	global_load_dwordx4 v[204:207], v[12:13], off
	v_lshl_add_u64 v[12:13], v[12:13], 0, s[8:9]
	s_waitcnt vmcnt(15)
	v_lshlrev_b32_e32 v20, 16, v208
	v_and_b32_e32 v21, 0xffff0000, v208
	v_lshlrev_b32_e32 v22, 16, v209
	v_and_b32_e32 v23, 0xffff0000, v209
	v_lshlrev_b32_e32 v24, 16, v210
	v_and_b32_e32 v25, 0xffff0000, v210
	v_lshlrev_b32_e32 v26, 16, v211
	v_and_b32_e32 v27, 0xffff0000, v211
	v_pk_fma_f32 v[8:9], v[20:21], v[20:21], v[8:9]
	v_pk_fma_f32 v[6:7], v[22:23], v[22:23], v[6:7]
	v_pk_fma_f32 v[4:5], v[24:25], v[24:25], v[4:5]
	v_pk_fma_f32 v[2:3], v[26:27], v[26:27], v[2:3]
	global_load_dwordx4 v[208:211], v[12:13], off
	v_lshl_add_u64 v[12:13], v[12:13], 0, s[8:9]
	s_waitcnt vmcnt(15)
	v_lshlrev_b32_e32 v20, 16, v212
	v_and_b32_e32 v21, 0xffff0000, v212
	v_lshlrev_b32_e32 v22, 16, v213
	v_and_b32_e32 v23, 0xffff0000, v213
	v_lshlrev_b32_e32 v24, 16, v214
	v_and_b32_e32 v25, 0xffff0000, v214
	v_lshlrev_b32_e32 v26, 16, v215
	v_and_b32_e32 v27, 0xffff0000, v215
	v_pk_fma_f32 v[8:9], v[20:21], v[20:21], v[8:9]
	v_pk_fma_f32 v[6:7], v[22:23], v[22:23], v[6:7]
	v_pk_fma_f32 v[4:5], v[24:25], v[24:25], v[4:5]
	v_pk_fma_f32 v[2:3], v[26:27], v[26:27], v[2:3]
	global_load_dwordx4 v[212:215], v[12:13], off
	v_lshl_add_u64 v[12:13], v[12:13], 0, s[8:9]
	s_waitcnt vmcnt(15)
	v_lshlrev_b32_e32 v20, 16, v216
	v_and_b32_e32 v21, 0xffff0000, v216
	v_lshlrev_b32_e32 v22, 16, v217
	v_and_b32_e32 v23, 0xffff0000, v217
	v_lshlrev_b32_e32 v24, 16, v218
	v_and_b32_e32 v25, 0xffff0000, v218
	v_lshlrev_b32_e32 v26, 16, v219
	v_and_b32_e32 v27, 0xffff0000, v219
	v_pk_fma_f32 v[8:9], v[20:21], v[20:21], v[8:9]
	v_pk_fma_f32 v[6:7], v[22:23], v[22:23], v[6:7]
	v_pk_fma_f32 v[4:5], v[24:25], v[24:25], v[4:5]
	v_pk_fma_f32 v[2:3], v[26:27], v[26:27], v[2:3]
	global_load_dwordx4 v[216:219], v[12:13], off
	v_lshl_add_u64 v[12:13], v[12:13], 0, s[8:9]
	s_waitcnt vmcnt(15)
	v_lshlrev_b32_e32 v20, 16, v220
	v_and_b32_e32 v21, 0xffff0000, v220
	v_lshlrev_b32_e32 v22, 16, v221
	v_and_b32_e32 v23, 0xffff0000, v221
	v_lshlrev_b32_e32 v24, 16, v222
	v_and_b32_e32 v25, 0xffff0000, v222
	v_lshlrev_b32_e32 v26, 16, v223
	v_and_b32_e32 v27, 0xffff0000, v223
	v_pk_fma_f32 v[8:9], v[20:21], v[20:21], v[8:9]
	v_pk_fma_f32 v[6:7], v[22:23], v[22:23], v[6:7]
	v_pk_fma_f32 v[4:5], v[24:25], v[24:25], v[4:5]
	v_pk_fma_f32 v[2:3], v[26:27], v[26:27], v[2:3]
	global_load_dwordx4 v[220:223], v[12:13], off
	v_lshl_add_u64 v[12:13], v[12:13], 0, s[8:9]
	s_waitcnt vmcnt(15)
	v_lshlrev_b32_e32 v20, 16, v224
	v_and_b32_e32 v21, 0xffff0000, v224
	v_lshlrev_b32_e32 v22, 16, v225
	v_and_b32_e32 v23, 0xffff0000, v225
	v_lshlrev_b32_e32 v24, 16, v226
	v_and_b32_e32 v25, 0xffff0000, v226
	v_lshlrev_b32_e32 v26, 16, v227
	v_and_b32_e32 v27, 0xffff0000, v227
	v_pk_fma_f32 v[8:9], v[20:21], v[20:21], v[8:9]
	v_pk_fma_f32 v[6:7], v[22:23], v[22:23], v[6:7]
	v_pk_fma_f32 v[4:5], v[24:25], v[24:25], v[4:5]
	v_pk_fma_f32 v[2:3], v[26:27], v[26:27], v[2:3]
	global_load_dwordx4 v[224:227], v[12:13], off
	v_lshl_add_u64 v[12:13], v[12:13], 0, s[8:9]
	s_waitcnt vmcnt(15)
	v_lshlrev_b32_e32 v20, 16, v228
	v_and_b32_e32 v21, 0xffff0000, v228
	v_lshlrev_b32_e32 v22, 16, v229
	v_and_b32_e32 v23, 0xffff0000, v229
	v_lshlrev_b32_e32 v24, 16, v230
	v_and_b32_e32 v25, 0xffff0000, v230
	v_lshlrev_b32_e32 v26, 16, v231
	v_and_b32_e32 v27, 0xffff0000, v231
	v_pk_fma_f32 v[8:9], v[20:21], v[20:21], v[8:9]
	v_pk_fma_f32 v[6:7], v[22:23], v[22:23], v[6:7]
	v_pk_fma_f32 v[4:5], v[24:25], v[24:25], v[4:5]
	v_pk_fma_f32 v[2:3], v[26:27], v[26:27], v[2:3]
	global_load_dwordx4 v[228:231], v[12:13], off
	v_lshl_add_u64 v[12:13], v[12:13], 0, s[8:9]
	s_waitcnt vmcnt(15)
	v_lshlrev_b32_e32 v20, 16, v232
	v_and_b32_e32 v21, 0xffff0000, v232
	v_lshlrev_b32_e32 v22, 16, v233
	v_and_b32_e32 v23, 0xffff0000, v233
	v_lshlrev_b32_e32 v24, 16, v234
	v_and_b32_e32 v25, 0xffff0000, v234
	v_lshlrev_b32_e32 v26, 16, v235
	v_and_b32_e32 v27, 0xffff0000, v235
	v_pk_fma_f32 v[8:9], v[20:21], v[20:21], v[8:9]
	v_pk_fma_f32 v[6:7], v[22:23], v[22:23], v[6:7]
	v_pk_fma_f32 v[4:5], v[24:25], v[24:25], v[4:5]
	v_pk_fma_f32 v[2:3], v[26:27], v[26:27], v[2:3]
	global_load_dwordx4 v[232:235], v[12:13], off
	v_lshl_add_u64 v[12:13], v[12:13], 0, s[8:9]
	s_waitcnt vmcnt(15)
	v_lshlrev_b32_e32 v20, 16, v236
	v_and_b32_e32 v21, 0xffff0000, v236
	v_lshlrev_b32_e32 v22, 16, v237
	v_and_b32_e32 v23, 0xffff0000, v237
	v_lshlrev_b32_e32 v24, 16, v238
	v_and_b32_e32 v25, 0xffff0000, v238
	v_lshlrev_b32_e32 v26, 16, v239
	v_and_b32_e32 v27, 0xffff0000, v239
	v_pk_fma_f32 v[8:9], v[20:21], v[20:21], v[8:9]
	v_pk_fma_f32 v[6:7], v[22:23], v[22:23], v[6:7]
	v_pk_fma_f32 v[4:5], v[24:25], v[24:25], v[4:5]
	v_pk_fma_f32 v[2:3], v[26:27], v[26:27], v[2:3]
	global_load_dwordx4 v[236:239], v[12:13], off
	v_lshl_add_u64 v[12:13], v[12:13], 0, s[8:9]
	s_waitcnt vmcnt(15)
	v_lshlrev_b32_e32 v20, 16, v176
	v_and_b32_e32 v21, 0xffff0000, v176
	v_lshlrev_b32_e32 v22, 16, v177
	v_and_b32_e32 v23, 0xffff0000, v177
	v_lshlrev_b32_e32 v24, 16, v178
	v_and_b32_e32 v25, 0xffff0000, v178
	v_lshlrev_b32_e32 v26, 16, v179
	v_and_b32_e32 v27, 0xffff0000, v179
	v_pk_fma_f32 v[8:9], v[20:21], v[20:21], v[8:9]
	v_pk_fma_f32 v[6:7], v[22:23], v[22:23], v[6:7]
	v_pk_fma_f32 v[4:5], v[24:25], v[24:25], v[4:5]
	v_pk_fma_f32 v[2:3], v[26:27], v[26:27], v[2:3]
	s_waitcnt vmcnt(14)
	v_lshlrev_b32_e32 v20, 16, v180
	v_and_b32_e32 v21, 0xffff0000, v180
	v_lshlrev_b32_e32 v22, 16, v181
	v_and_b32_e32 v23, 0xffff0000, v181
	v_lshlrev_b32_e32 v24, 16, v182
	v_and_b32_e32 v25, 0xffff0000, v182
	v_lshlrev_b32_e32 v26, 16, v183
	v_and_b32_e32 v27, 0xffff0000, v183
	v_pk_fma_f32 v[8:9], v[20:21], v[20:21], v[8:9]
	v_pk_fma_f32 v[6:7], v[22:23], v[22:23], v[6:7]
	v_pk_fma_f32 v[4:5], v[24:25], v[24:25], v[4:5]
	v_pk_fma_f32 v[2:3], v[26:27], v[26:27], v[2:3]
	s_waitcnt vmcnt(13)
	v_lshlrev_b32_e32 v20, 16, v184
	v_and_b32_e32 v21, 0xffff0000, v184
	v_lshlrev_b32_e32 v22, 16, v185
	v_and_b32_e32 v23, 0xffff0000, v185
	v_lshlrev_b32_e32 v24, 16, v186
	v_and_b32_e32 v25, 0xffff0000, v186
	v_lshlrev_b32_e32 v26, 16, v187
	v_and_b32_e32 v27, 0xffff0000, v187
	v_pk_fma_f32 v[8:9], v[20:21], v[20:21], v[8:9]
	v_pk_fma_f32 v[6:7], v[22:23], v[22:23], v[6:7]
	v_pk_fma_f32 v[4:5], v[24:25], v[24:25], v[4:5]
	v_pk_fma_f32 v[2:3], v[26:27], v[26:27], v[2:3]
	s_waitcnt vmcnt(12)
	v_lshlrev_b32_e32 v20, 16, v188
	v_and_b32_e32 v21, 0xffff0000, v188
	v_lshlrev_b32_e32 v22, 16, v189
	v_and_b32_e32 v23, 0xffff0000, v189
	v_lshlrev_b32_e32 v24, 16, v190
	v_and_b32_e32 v25, 0xffff0000, v190
	v_lshlrev_b32_e32 v26, 16, v191
	v_and_b32_e32 v27, 0xffff0000, v191
	v_pk_fma_f32 v[8:9], v[20:21], v[20:21], v[8:9]
	v_pk_fma_f32 v[6:7], v[22:23], v[22:23], v[6:7]
	v_pk_fma_f32 v[4:5], v[24:25], v[24:25], v[4:5]
	v_pk_fma_f32 v[2:3], v[26:27], v[26:27], v[2:3]
	s_waitcnt vmcnt(11)
	v_lshlrev_b32_e32 v20, 16, v192
	v_and_b32_e32 v21, 0xffff0000, v192
	v_lshlrev_b32_e32 v22, 16, v193
	v_and_b32_e32 v23, 0xffff0000, v193
	v_lshlrev_b32_e32 v24, 16, v194
	v_and_b32_e32 v25, 0xffff0000, v194
	v_lshlrev_b32_e32 v26, 16, v195
	v_and_b32_e32 v27, 0xffff0000, v195
	v_pk_fma_f32 v[8:9], v[20:21], v[20:21], v[8:9]
	v_pk_fma_f32 v[6:7], v[22:23], v[22:23], v[6:7]
	v_pk_fma_f32 v[4:5], v[24:25], v[24:25], v[4:5]
	v_pk_fma_f32 v[2:3], v[26:27], v[26:27], v[2:3]
	s_waitcnt vmcnt(10)
	v_lshlrev_b32_e32 v20, 16, v196
	v_and_b32_e32 v21, 0xffff0000, v196
	v_lshlrev_b32_e32 v22, 16, v197
	v_and_b32_e32 v23, 0xffff0000, v197
	v_lshlrev_b32_e32 v24, 16, v198
	v_and_b32_e32 v25, 0xffff0000, v198
	v_lshlrev_b32_e32 v26, 16, v199
	v_and_b32_e32 v27, 0xffff0000, v199
	v_pk_fma_f32 v[8:9], v[20:21], v[20:21], v[8:9]
	v_pk_fma_f32 v[6:7], v[22:23], v[22:23], v[6:7]
	v_pk_fma_f32 v[4:5], v[24:25], v[24:25], v[4:5]
	v_pk_fma_f32 v[2:3], v[26:27], v[26:27], v[2:3]
	s_waitcnt vmcnt(9)
	v_lshlrev_b32_e32 v20, 16, v200
	v_and_b32_e32 v21, 0xffff0000, v200
	v_lshlrev_b32_e32 v22, 16, v201
	v_and_b32_e32 v23, 0xffff0000, v201
	v_lshlrev_b32_e32 v24, 16, v202
	v_and_b32_e32 v25, 0xffff0000, v202
	v_lshlrev_b32_e32 v26, 16, v203
	v_and_b32_e32 v27, 0xffff0000, v203
	v_pk_fma_f32 v[8:9], v[20:21], v[20:21], v[8:9]
	v_pk_fma_f32 v[6:7], v[22:23], v[22:23], v[6:7]
	v_pk_fma_f32 v[4:5], v[24:25], v[24:25], v[4:5]
	v_pk_fma_f32 v[2:3], v[26:27], v[26:27], v[2:3]
	s_waitcnt vmcnt(8)
	v_lshlrev_b32_e32 v20, 16, v204
	v_and_b32_e32 v21, 0xffff0000, v204
	v_lshlrev_b32_e32 v22, 16, v205
	v_and_b32_e32 v23, 0xffff0000, v205
	v_lshlrev_b32_e32 v24, 16, v206
	v_and_b32_e32 v25, 0xffff0000, v206
	v_lshlrev_b32_e32 v26, 16, v207
	v_and_b32_e32 v27, 0xffff0000, v207
	v_pk_fma_f32 v[8:9], v[20:21], v[20:21], v[8:9]
	v_pk_fma_f32 v[6:7], v[22:23], v[22:23], v[6:7]
	v_pk_fma_f32 v[4:5], v[24:25], v[24:25], v[4:5]
	v_pk_fma_f32 v[2:3], v[26:27], v[26:27], v[2:3]
	s_waitcnt vmcnt(7)
	v_lshlrev_b32_e32 v20, 16, v208
	v_and_b32_e32 v21, 0xffff0000, v208
	v_lshlrev_b32_e32 v22, 16, v209
	v_and_b32_e32 v23, 0xffff0000, v209
	v_lshlrev_b32_e32 v24, 16, v210
	v_and_b32_e32 v25, 0xffff0000, v210
	v_lshlrev_b32_e32 v26, 16, v211
	v_and_b32_e32 v27, 0xffff0000, v211
	v_pk_fma_f32 v[8:9], v[20:21], v[20:21], v[8:9]
	v_pk_fma_f32 v[6:7], v[22:23], v[22:23], v[6:7]
	v_pk_fma_f32 v[4:5], v[24:25], v[24:25], v[4:5]
	v_pk_fma_f32 v[2:3], v[26:27], v[26:27], v[2:3]
	s_waitcnt vmcnt(6)
	v_lshlrev_b32_e32 v20, 16, v212
	v_and_b32_e32 v21, 0xffff0000, v212
	v_lshlrev_b32_e32 v22, 16, v213
	v_and_b32_e32 v23, 0xffff0000, v213
	v_lshlrev_b32_e32 v24, 16, v214
	v_and_b32_e32 v25, 0xffff0000, v214
	v_lshlrev_b32_e32 v26, 16, v215
	v_and_b32_e32 v27, 0xffff0000, v215
	v_pk_fma_f32 v[8:9], v[20:21], v[20:21], v[8:9]
	v_pk_fma_f32 v[6:7], v[22:23], v[22:23], v[6:7]
	v_pk_fma_f32 v[4:5], v[24:25], v[24:25], v[4:5]
	v_pk_fma_f32 v[2:3], v[26:27], v[26:27], v[2:3]
	s_waitcnt vmcnt(5)
	v_lshlrev_b32_e32 v20, 16, v216
	v_and_b32_e32 v21, 0xffff0000, v216
	v_lshlrev_b32_e32 v22, 16, v217
	v_and_b32_e32 v23, 0xffff0000, v217
	v_lshlrev_b32_e32 v24, 16, v218
	v_and_b32_e32 v25, 0xffff0000, v218
	v_lshlrev_b32_e32 v26, 16, v219
	v_and_b32_e32 v27, 0xffff0000, v219
	v_pk_fma_f32 v[8:9], v[20:21], v[20:21], v[8:9]
	v_pk_fma_f32 v[6:7], v[22:23], v[22:23], v[6:7]
	v_pk_fma_f32 v[4:5], v[24:25], v[24:25], v[4:5]
	v_pk_fma_f32 v[2:3], v[26:27], v[26:27], v[2:3]
	s_waitcnt vmcnt(4)
	v_lshlrev_b32_e32 v20, 16, v220
	v_and_b32_e32 v21, 0xffff0000, v220
	v_lshlrev_b32_e32 v22, 16, v221
	v_and_b32_e32 v23, 0xffff0000, v221
	v_lshlrev_b32_e32 v24, 16, v222
	v_and_b32_e32 v25, 0xffff0000, v222
	v_lshlrev_b32_e32 v26, 16, v223
	v_and_b32_e32 v27, 0xffff0000, v223
	v_pk_fma_f32 v[8:9], v[20:21], v[20:21], v[8:9]
	v_pk_fma_f32 v[6:7], v[22:23], v[22:23], v[6:7]
	v_pk_fma_f32 v[4:5], v[24:25], v[24:25], v[4:5]
	v_pk_fma_f32 v[2:3], v[26:27], v[26:27], v[2:3]
	s_waitcnt vmcnt(3)
	v_lshlrev_b32_e32 v20, 16, v224
	v_and_b32_e32 v21, 0xffff0000, v224
	v_lshlrev_b32_e32 v22, 16, v225
	v_and_b32_e32 v23, 0xffff0000, v225
	v_lshlrev_b32_e32 v24, 16, v226
	v_and_b32_e32 v25, 0xffff0000, v226
	v_lshlrev_b32_e32 v26, 16, v227
	v_and_b32_e32 v27, 0xffff0000, v227
	v_pk_fma_f32 v[8:9], v[20:21], v[20:21], v[8:9]
	v_pk_fma_f32 v[6:7], v[22:23], v[22:23], v[6:7]
	v_pk_fma_f32 v[4:5], v[24:25], v[24:25], v[4:5]
	v_pk_fma_f32 v[2:3], v[26:27], v[26:27], v[2:3]
	s_waitcnt vmcnt(2)
	v_lshlrev_b32_e32 v20, 16, v228
	v_and_b32_e32 v21, 0xffff0000, v228
	v_lshlrev_b32_e32 v22, 16, v229
	v_and_b32_e32 v23, 0xffff0000, v229
	v_lshlrev_b32_e32 v24, 16, v230
	v_and_b32_e32 v25, 0xffff0000, v230
	v_lshlrev_b32_e32 v26, 16, v231
	v_and_b32_e32 v27, 0xffff0000, v231
	v_pk_fma_f32 v[8:9], v[20:21], v[20:21], v[8:9]
	v_pk_fma_f32 v[6:7], v[22:23], v[22:23], v[6:7]
	v_pk_fma_f32 v[4:5], v[24:25], v[24:25], v[4:5]
	v_pk_fma_f32 v[2:3], v[26:27], v[26:27], v[2:3]
	s_waitcnt vmcnt(1)
	v_lshlrev_b32_e32 v20, 16, v232
	v_and_b32_e32 v21, 0xffff0000, v232
	v_lshlrev_b32_e32 v22, 16, v233
	v_and_b32_e32 v23, 0xffff0000, v233
	v_lshlrev_b32_e32 v24, 16, v234
	v_and_b32_e32 v25, 0xffff0000, v234
	v_lshlrev_b32_e32 v26, 16, v235
	v_and_b32_e32 v27, 0xffff0000, v235
	v_pk_fma_f32 v[8:9], v[20:21], v[20:21], v[8:9]
	v_pk_fma_f32 v[6:7], v[22:23], v[22:23], v[6:7]
	v_pk_fma_f32 v[4:5], v[24:25], v[24:25], v[4:5]
	v_pk_fma_f32 v[2:3], v[26:27], v[26:27], v[2:3]
	s_waitcnt vmcnt(0)
	v_lshlrev_b32_e32 v20, 16, v236
	v_and_b32_e32 v21, 0xffff0000, v236
	v_lshlrev_b32_e32 v22, 16, v237
	v_and_b32_e32 v23, 0xffff0000, v237
	v_lshlrev_b32_e32 v24, 16, v238
	v_and_b32_e32 v25, 0xffff0000, v238
	v_lshlrev_b32_e32 v26, 16, v239
	v_and_b32_e32 v27, 0xffff0000, v239
	v_pk_fma_f32 v[8:9], v[20:21], v[20:21], v[8:9]
	v_pk_fma_f32 v[6:7], v[22:23], v[22:23], v[6:7]
	v_pk_fma_f32 v[4:5], v[24:25], v[24:25], v[4:5]
	v_pk_fma_f32 v[2:3], v[26:27], v[26:27], v[2:3]
	v_and_b32_e32 v10, 64, v114
	v_xor_b32_e32 v1, 16, v114
	v_add_u32_e32 v12, 64, v10
	v_cmp_lt_i32_e32 vcc, v1, v12
	v_xor_b32_e32 v13, 32, v114
	s_nop 0
	v_cndmask_b32_e32 v1, v114, v1, vcc
	v_cmp_lt_i32_e32 vcc, v13, v12
	v_lshlrev_b32_e32 v1, 2, v1
	v_mov_b32_e32 v10, v8
	s_nop 1
	v_permlane16_swap_b32_e32 v8, v10
	v_cndmask_b32_e32 v14, v114, v13, vcc
	v_mov_b32_e32 v11, v9
	s_nop 1
	v_permlane16_swap_b32_e32 v9, v11
	v_mov_b32_e32 v12, v6
	s_nop 1
	v_permlane16_swap_b32_e32 v6, v12
	v_mov_b32_e32 v13, v7
	s_nop 1
	v_permlane16_swap_b32_e32 v7, v13
	v_lshlrev_b32_e32 v19, 2, v14
	v_mov_b32_e32 v14, v4
	s_nop 1
	v_permlane16_swap_b32_e32 v4, v14
	v_mov_b32_e32 v15, v5
	s_nop 1
	v_permlane16_swap_b32_e32 v5, v15
	v_mov_b32_e32 v16, v2
	s_nop 1
	v_permlane16_swap_b32_e32 v2, v16
	v_mov_b32_e32 v17, v3
	s_nop 1
	v_permlane16_swap_b32_e32 v3, v17
	s_waitcnt lgkmcnt(6)
	v_pk_add_f32 v[8:9], v[8:9], v[10:11]
	s_waitcnt lgkmcnt(4)
	v_pk_add_f32 v[6:7], v[6:7], v[12:13]
	s_waitcnt lgkmcnt(2)
	v_pk_add_f32 v[4:5], v[4:5], v[14:15]
	v_mov_b32_e32 v10, v8
	s_nop 1
	v_permlane32_swap_b32_e32 v8, v10
	s_waitcnt lgkmcnt(1)
	v_pk_add_f32 v[2:3], v[2:3], v[16:17]
	v_mov_b32_e32 v11, v9
	s_nop 1
	v_permlane32_swap_b32_e32 v9, v11
	v_mov_b32_e32 v12, v6
	s_nop 1
	v_permlane32_swap_b32_e32 v6, v12
	v_mov_b32_e32 v13, v7
	s_nop 1
	v_permlane32_swap_b32_e32 v7, v13
	v_mov_b32_e32 v14, v4
	s_nop 1
	v_permlane32_swap_b32_e32 v4, v14
	v_mov_b32_e32 v15, v5
	s_nop 1
	v_permlane32_swap_b32_e32 v5, v15
	v_mov_b32_e32 v16, v2
	s_nop 1
	v_permlane32_swap_b32_e32 v2, v16
	v_mov_b32_e32 v17, v3
	s_nop 1
	v_permlane32_swap_b32_e32 v3, v17
	v_bfe_u32 v19, v18, 4, 2
	v_and_b32_e32 v1, 15, v18
	v_cmp_eq_u32_e32 vcc, 0, v19
	s_and_saveexec_b64 s[8:9], vcc
	s_cbranch_execz .LBB0_393
	v_lshlrev_b32_e32 v20, 3, v18
	v_and_b32_e32 v20, 0xfffffe00, v20
	v_lshlrev_b32_e32 v21, 5, v1
	v_add3_u32 v20, 0, v20, v21
	s_waitcnt lgkmcnt(6)
	v_pk_add_f32 v[8:9], v[8:9], v[10:11]
	s_waitcnt lgkmcnt(4)
	v_pk_add_f32 v[10:11], v[6:7], v[12:13]
	s_waitcnt lgkmcnt(2)
	v_pk_add_f32 v[4:5], v[4:5], v[14:15]
	s_waitcnt lgkmcnt(0)
	v_pk_add_f32 v[6:7], v[2:3], v[16:17]
	ds_write_b128 v20, v[8:11]
	ds_write_b128 v20, v[4:7] offset:16
